# EpiPool epilogue: gate loads prefetched in two batches of 8 with counted vmcnt (s[12:13] flag restored), on top of opt11
# speedup vs baseline: 1.0133x; 1.0133x over previous
; #define LAS __attribute__((address_space(3)))
; __device__ __forceinline__ float bflo(unsigned w) { return __uint_as_float(w << 16); }
; __device__ __forceinline__ float bfhi(unsigned w) { return __uint_as_float(w & 0xffff0000u); }
;     __device__ __forceinline__ void operator()(const f32x4 (&acc)[2][2][4][2], const Unit& u, int wr, int wc, int fr, int fq, const LAS float* rsl) const {
;         const int row0 = u.pm * 256 + wr * 64 + fr;
; #pragma unroll
;         for (int bj = 0; bj < 2; ++bj) {
;             const int col = u.pn * 256 + bj * 128 + wc * 32 + 8 * fq;
;             const f32x4 p0 = *(const f32x4*)(pscale + col), p1 = *(const f32x4*)(pscale + col + 4);
; #pragma unroll
;             for (int ai = 0; ai < 2; ++ai)
; #pragma unroll
;                 for (int m = 0; m < 4; ++m) {
;                     const int row = row0 + ai * 128 + m * 16;
;                     bf16_t* ptr = P + (size_t)row * PW + 1024 + col;
;                     const u32x4 g = *(const u32x4*)ptr;
;                     f32x4 v0 = acc[ai][bj][m][0] * p0, v1 = acc[ai][bj][m][1] * p1;
;                     v0[0] *= bflo(g.x); v0[1] *= bfhi(g.x); v0[2] *= bflo(g.y); v0[3] *= bfhi(g.y);
;                     v1[0] *= bflo(g.z); v1[1] *= bfhi(g.z); v1[2] *= bflo(g.w); v1[3] *= bfhi(g.w);
;                     *(u32x4*)ptr = pack8(v0, v1);
.LBB0_288:
	v_lshl_or_b32 v158, s52, 8, v168
	v_lshl_add_u32 v170, s26, 8, v166
	v_ashrrev_i32_e32 v159, 31, v158
	v_mov_b64_e32 v[162:163], s[72:73]
	v_mad_i64_i32 v[172:173], s[12:13], v170, s80, v[162:163]
	v_lshlrev_b64 v[164:165], 1, v[158:159]
	v_lshl_add_u64 v[160:161], v[158:159], 2, s[2:3]
	v_lshl_add_u64 v[158:159], v[172:173], 0, v[164:165]
	global_load_dwordx4 v[112:115], v[160:161], off offset:16
	global_load_dwordx4 v[116:119], v[160:161], off
	v_mbcnt_lo_u32_b32 v173, -1, 0
	v_mbcnt_hi_u32_b32 v173, -1, v173
	v_and_b32_e32 v172, 15, v173
	v_lshrrev_b32_e32 v173, 4, v173
	v_mul_u32_u24_e32 v172, 0x1c00, v172
	v_readfirstlane_b32 s12, v158
	v_readfirstlane_b32 s13, v159
	v_lshl_or_b32 v172, v173, 4, v172
	s_nop 4
	global_load_dwordx4 v[178:181], v172, s[12:13] offset:2048
	s_add_u32 s12, s12, 0x1c000
	s_addc_u32 s13, s13, 0
	global_load_dwordx4 v[182:185], v172, s[12:13] offset:2048
	s_add_u32 s12, s12, 0x1c000
	s_addc_u32 s13, s13, 0
	global_load_dwordx4 v[186:189], v172, s[12:13] offset:2048
	s_add_u32 s12, s12, 0x1c000
	s_addc_u32 s13, s13, 0
	global_load_dwordx4 v[190:193], v172, s[12:13] offset:2048
	s_add_u32 s12, s12, 0x8c000
	s_addc_u32 s13, s13, 0
	global_load_dwordx4 v[194:197], v172, s[12:13] offset:2048
	s_add_u32 s12, s12, 0x1c000
	s_addc_u32 s13, s13, 0
	global_load_dwordx4 v[198:201], v172, s[12:13] offset:2048
	s_add_u32 s12, s12, 0x1c000
	s_addc_u32 s13, s13, 0
	global_load_dwordx4 v[202:205], v172, s[12:13] offset:2048
	s_add_u32 s12, s12, 0x1c000
	s_addc_u32 s13, s13, 0
	global_load_dwordx4 v[206:209], v172, s[12:13] offset:2048
	s_waitcnt vmcnt(7)
	s_nop 1
	v_mov_b32_e32 v172, v178
	v_mov_b32_e32 v173, v179
	v_mov_b32_e32 v174, v180
	v_mov_b32_e32 v175, v181
	s_and_b64 vcc, exec, s[10:11]
	v_pk_mul_f32 v[132:133], v[132:133], v[112:113]
	v_pk_mul_f32 v[130:131], v[130:131], v[118:119]
	v_lshlrev_b32_e32 v176, 16, v172
	v_and_b32_e32 v177, 0xffff0000, v172
	v_lshlrev_b32_e32 v172, 16, v173
	v_and_b32_e32 v173, 0xffff0000, v173
	v_pk_mul_f32 v[130:131], v[130:131], v[172:173]
	v_lshlrev_b32_e32 v172, 16, v174
	v_and_b32_e32 v173, 0xffff0000, v174
	v_pk_mul_f32 v[128:129], v[128:129], v[116:117]
	v_pk_mul_f32 v[134:135], v[134:135], v[114:115]
	v_pk_mul_f32 v[132:133], v[132:133], v[172:173]
	v_lshlrev_b32_e32 v172, 16, v175
	v_and_b32_e32 v173, 0xffff0000, v175
	v_pk_mul_f32 v[128:129], v[128:129], v[176:177]
	v_pk_mul_f32 v[134:135], v[134:135], v[172:173]
	v_cvt_pk_bf16_f32 v128, v128, v129
	v_cvt_pk_bf16_f32 v129, v130, v131
	v_cvt_pk_bf16_f32 v130, v132, v133
	v_cvt_pk_bf16_f32 v131, v134, v135
	global_store_dwordx4 v[158:159], v[128:131], off offset:2048
	v_pk_mul_f32 v[126:127], v[126:127], v[118:119]
	v_pk_mul_f32 v[120:121], v[120:121], v[112:113]
	v_or_b32_e32 v128, 16, v170
	v_mad_i64_i32 v[128:129], s[12:13], v128, s80, v[162:163]
	v_lshl_add_u64 v[128:129], v[128:129], 0, v[164:165]
	s_waitcnt vmcnt(7)
	s_nop 1
	v_mov_b32_e32 v130, v182
	v_mov_b32_e32 v131, v183
	v_mov_b32_e32 v132, v184
	v_mov_b32_e32 v133, v185
	v_pk_mul_f32 v[124:125], v[124:125], v[116:117]
	v_pk_mul_f32 v[122:123], v[122:123], v[114:115]
	v_pk_mul_f32 v[110:111], v[110:111], v[118:119]
	v_pk_mul_f32 v[104:105], v[104:105], v[112:113]
	v_pk_mul_f32 v[108:109], v[108:109], v[116:117]
	v_pk_mul_f32 v[106:107], v[106:107], v[114:115]
	v_pk_mul_f32 v[102:103], v[102:103], v[118:119]
	v_pk_mul_f32 v[96:97], v[96:97], v[112:113]
	v_pk_mul_f32 v[100:101], v[100:101], v[116:117]
	v_pk_mul_f32 v[98:99], v[98:99], v[114:115]
	v_pk_mul_f32 v[94:95], v[94:95], v[118:119]
	v_pk_mul_f32 v[88:89], v[88:89], v[112:113]
	v_pk_mul_f32 v[92:93], v[92:93], v[116:117]
	v_pk_mul_f32 v[90:91], v[90:91], v[114:115]
	v_pk_mul_f32 v[86:87], v[86:87], v[118:119]
	v_pk_mul_f32 v[80:81], v[80:81], v[112:113]
	v_pk_mul_f32 v[84:85], v[84:85], v[116:117]
	v_pk_mul_f32 v[82:83], v[82:83], v[114:115]
	v_pk_mul_f32 v[78:79], v[78:79], v[118:119]
	v_pk_mul_f32 v[72:73], v[72:73], v[112:113]
	v_pk_mul_f32 v[76:77], v[76:77], v[116:117]
	v_pk_mul_f32 v[74:75], v[74:75], v[114:115]
	v_pk_mul_f32 v[70:71], v[70:71], v[118:119]
	v_pk_mul_f32 v[64:65], v[64:65], v[112:113]
	v_pk_mul_f32 v[68:69], v[68:69], v[116:117]
	v_pk_mul_f32 v[66:67], v[66:67], v[114:115]
	v_lshlrev_b32_e32 v134, 16, v130
	v_and_b32_e32 v135, 0xffff0000, v130
	v_lshlrev_b32_e32 v130, 16, v131
	v_and_b32_e32 v131, 0xffff0000, v131
	v_pk_mul_f32 v[126:127], v[126:127], v[130:131]
	v_lshlrev_b32_e32 v130, 16, v132
	v_and_b32_e32 v131, 0xffff0000, v132
	v_pk_mul_f32 v[130:131], v[120:121], v[130:131]
	v_lshlrev_b32_e32 v120, 16, v133
	v_and_b32_e32 v121, 0xffff0000, v133
	v_pk_mul_f32 v[124:125], v[124:125], v[134:135]
	v_pk_mul_f32 v[132:133], v[122:123], v[120:121]
	v_cvt_pk_bf16_f32 v120, v124, v125
	v_cvt_pk_bf16_f32 v121, v126, v127
	v_cvt_pk_bf16_f32 v122, v130, v131
	v_cvt_pk_bf16_f32 v123, v132, v133
	global_store_dwordx4 v[128:129], v[120:123], off offset:2048
	s_nop 1
	v_or_b32_e32 v120, 32, v170
	v_mad_i64_i32 v[120:121], s[12:13], v120, s80, v[162:163]
	v_lshl_add_u64 v[120:121], v[120:121], 0, v[164:165]
	s_waitcnt vmcnt(7)
	s_nop 1
	v_mov_b32_e32 v122, v186
	v_mov_b32_e32 v123, v187
	v_mov_b32_e32 v124, v188
	v_mov_b32_e32 v125, v189
	v_lshlrev_b32_e32 v126, 16, v122
	v_and_b32_e32 v127, 0xffff0000, v122
	v_lshlrev_b32_e32 v122, 16, v123
	v_and_b32_e32 v123, 0xffff0000, v123
	v_pk_mul_f32 v[110:111], v[110:111], v[122:123]
	v_lshlrev_b32_e32 v122, 16, v124
	v_and_b32_e32 v123, 0xffff0000, v124
	v_pk_mul_f32 v[122:123], v[104:105], v[122:123]
	v_lshlrev_b32_e32 v104, 16, v125
	v_and_b32_e32 v105, 0xffff0000, v125
	v_pk_mul_f32 v[108:109], v[108:109], v[126:127]
	v_pk_mul_f32 v[124:125], v[106:107], v[104:105]
	v_cvt_pk_bf16_f32 v104, v108, v109
	v_cvt_pk_bf16_f32 v105, v110, v111
	v_cvt_pk_bf16_f32 v106, v122, v123
	v_cvt_pk_bf16_f32 v107, v124, v125
	global_store_dwordx4 v[120:121], v[104:107], off offset:2048
	s_nop 1
	v_or_b32_e32 v104, 48, v170
	v_mad_i64_i32 v[104:105], s[12:13], v104, s80, v[162:163]
	v_lshl_add_u64 v[104:105], v[104:105], 0, v[164:165]
	s_waitcnt vmcnt(7)
; __device__ __forceinline__ float bflo(unsigned w) { return __uint_as_float(w << 16); }
; __device__ __forceinline__ float bfhi(unsigned w) { return __uint_as_float(w & 0xffff0000u); }
;     __device__ __forceinline__ void operator()(const f32x4 (&acc)[2][2][4][2], const Unit& u, int wr, int wc, int fr, int fq, const LAS float* rsl) const {
;     ...
;         for (int bj = 0; bj < 2; ++bj) {
;             const int col = u.pn * 256 + bj * 128 + wc * 32 + 8 * fq;
;             const f32x4 p0 = *(const f32x4*)(pscale + col), p1 = *(const f32x4*)(pscale + col + 4);
; #pragma unroll
;             for (int ai = 0; ai < 2; ++ai)
; #pragma unroll
;                 for (int m = 0; m < 4; ++m) {
;                     const int row = row0 + ai * 128 + m * 16;
;                     bf16_t* ptr = P + (size_t)row * PW + 1024 + col;
;                     const u32x4 g = *(const u32x4*)ptr;
;                     f32x4 v0 = acc[ai][bj][m][0] * p0, v1 = acc[ai][bj][m][1] * p1;
;                     v0[0] *= bflo(g.x); v0[1] *= bfhi(g.x); v0[2] *= bflo(g.y); v0[3] *= bfhi(g.y);
;                     v1[0] *= bflo(g.z); v1[1] *= bfhi(g.z); v1[2] *= bflo(g.w); v1[3] *= bfhi(g.w);
;                     *(u32x4*)ptr = pack8(v0, v1);
	s_nop 1
	v_mov_b32_e32 v106, v190
	v_mov_b32_e32 v107, v191
	v_mov_b32_e32 v108, v192
	v_mov_b32_e32 v109, v193
	v_lshlrev_b32_e32 v110, 16, v106
	v_and_b32_e32 v111, 0xffff0000, v106
	v_lshlrev_b32_e32 v106, 16, v107
	v_and_b32_e32 v107, 0xffff0000, v107
	v_pk_mul_f32 v[102:103], v[102:103], v[106:107]
	v_lshlrev_b32_e32 v106, 16, v108
	v_and_b32_e32 v107, 0xffff0000, v108
	v_pk_mul_f32 v[106:107], v[96:97], v[106:107]
	v_lshlrev_b32_e32 v96, 16, v109
	v_and_b32_e32 v97, 0xffff0000, v109
	v_pk_mul_f32 v[100:101], v[100:101], v[110:111]
	v_pk_mul_f32 v[108:109], v[98:99], v[96:97]
	v_cvt_pk_bf16_f32 v96, v100, v101
	v_cvt_pk_bf16_f32 v97, v102, v103
	v_cvt_pk_bf16_f32 v98, v106, v107
	v_cvt_pk_bf16_f32 v99, v108, v109
	global_store_dwordx4 v[104:105], v[96:99], off offset:2048
	s_nop 1
	v_add_u32_e32 v96, 0x80, v170
	v_mad_i64_i32 v[96:97], s[12:13], v96, s80, v[162:163]
	v_lshl_add_u64 v[96:97], v[96:97], 0, v[164:165]
	s_waitcnt vmcnt(7)
	s_nop 1
	v_mov_b32_e32 v98, v194
	v_mov_b32_e32 v99, v195
	v_mov_b32_e32 v100, v196
	v_mov_b32_e32 v101, v197
	v_lshlrev_b32_e32 v102, 16, v98
	v_and_b32_e32 v103, 0xffff0000, v98
	v_lshlrev_b32_e32 v98, 16, v99
	v_and_b32_e32 v99, 0xffff0000, v99
	v_pk_mul_f32 v[94:95], v[94:95], v[98:99]
	v_lshlrev_b32_e32 v98, 16, v100
	v_and_b32_e32 v99, 0xffff0000, v100
	v_pk_mul_f32 v[98:99], v[88:89], v[98:99]
	v_lshlrev_b32_e32 v88, 16, v101
	v_and_b32_e32 v89, 0xffff0000, v101
	v_pk_mul_f32 v[92:93], v[92:93], v[102:103]
	v_pk_mul_f32 v[100:101], v[90:91], v[88:89]
	v_cvt_pk_bf16_f32 v88, v92, v93
	v_cvt_pk_bf16_f32 v89, v94, v95
	v_cvt_pk_bf16_f32 v90, v98, v99
	v_cvt_pk_bf16_f32 v91, v100, v101
	global_store_dwordx4 v[96:97], v[88:91], off offset:2048
	s_nop 1
	v_add_u32_e32 v88, 0x90, v170
	v_mad_i64_i32 v[88:89], s[12:13], v88, s80, v[162:163]
	v_lshl_add_u64 v[88:89], v[88:89], 0, v[164:165]
	s_waitcnt vmcnt(7)
	s_nop 1
	v_mov_b32_e32 v90, v198
	v_mov_b32_e32 v91, v199
	v_mov_b32_e32 v92, v200
	v_mov_b32_e32 v93, v201
	v_lshlrev_b32_e32 v94, 16, v90
	v_and_b32_e32 v95, 0xffff0000, v90
	v_lshlrev_b32_e32 v90, 16, v91
	v_and_b32_e32 v91, 0xffff0000, v91
	v_pk_mul_f32 v[86:87], v[86:87], v[90:91]
	v_lshlrev_b32_e32 v90, 16, v92
	v_and_b32_e32 v91, 0xffff0000, v92
	v_pk_mul_f32 v[90:91], v[80:81], v[90:91]
	v_lshlrev_b32_e32 v80, 16, v93
	v_and_b32_e32 v81, 0xffff0000, v93
	v_pk_mul_f32 v[84:85], v[84:85], v[94:95]
	v_pk_mul_f32 v[92:93], v[82:83], v[80:81]
	v_cvt_pk_bf16_f32 v80, v84, v85
	v_cvt_pk_bf16_f32 v81, v86, v87
	v_cvt_pk_bf16_f32 v82, v90, v91
	v_cvt_pk_bf16_f32 v83, v92, v93
	global_store_dwordx4 v[88:89], v[80:83], off offset:2048
	s_nop 1
	v_add_u32_e32 v80, 0xa0, v170
	v_mad_i64_i32 v[80:81], s[12:13], v80, s80, v[162:163]
	v_lshl_add_u64 v[80:81], v[80:81], 0, v[164:165]
	s_waitcnt vmcnt(7)
	s_nop 1
	v_mov_b32_e32 v82, v202
	v_mov_b32_e32 v83, v203
	v_mov_b32_e32 v84, v204
	v_mov_b32_e32 v85, v205
	v_lshlrev_b32_e32 v86, 16, v82
	v_and_b32_e32 v87, 0xffff0000, v82
	v_lshlrev_b32_e32 v82, 16, v83
	v_and_b32_e32 v83, 0xffff0000, v83
	v_pk_mul_f32 v[78:79], v[78:79], v[82:83]
	v_lshlrev_b32_e32 v82, 16, v84
	v_and_b32_e32 v83, 0xffff0000, v84
	v_pk_mul_f32 v[82:83], v[72:73], v[82:83]
	v_lshlrev_b32_e32 v72, 16, v85
	v_and_b32_e32 v73, 0xffff0000, v85
	v_pk_mul_f32 v[76:77], v[76:77], v[86:87]
	v_pk_mul_f32 v[84:85], v[74:75], v[72:73]
	v_cvt_pk_bf16_f32 v72, v76, v77
	v_cvt_pk_bf16_f32 v73, v78, v79
	v_cvt_pk_bf16_f32 v74, v82, v83
	v_cvt_pk_bf16_f32 v75, v84, v85
	global_store_dwordx4 v[80:81], v[72:75], off offset:2048
	s_nop 1
	v_add_u32_e32 v72, 0xb0, v170
	v_mad_i64_i32 v[72:73], s[12:13], v72, s80, v[162:163]
	v_lshl_add_u64 v[72:73], v[72:73], 0, v[164:165]
	s_waitcnt vmcnt(7)
	s_nop 1
	v_mov_b32_e32 v74, v206
	v_mov_b32_e32 v75, v207
	v_mov_b32_e32 v76, v208
	v_mov_b32_e32 v77, v209
	s_mov_b64 s[12:13], -1
	v_lshlrev_b32_e32 v78, 16, v74
	v_and_b32_e32 v79, 0xffff0000, v74
	v_lshlrev_b32_e32 v74, 16, v75
	v_and_b32_e32 v75, 0xffff0000, v75
	v_pk_mul_f32 v[70:71], v[70:71], v[74:75]
	v_lshlrev_b32_e32 v74, 16, v76
	v_and_b32_e32 v75, 0xffff0000, v76
	v_pk_mul_f32 v[74:75], v[64:65], v[74:75]
	v_lshlrev_b32_e32 v64, 16, v77
	v_and_b32_e32 v65, 0xffff0000, v77
	v_pk_mul_f32 v[68:69], v[68:69], v[78:79]
	v_pk_mul_f32 v[76:77], v[66:67], v[64:65]
	v_cvt_pk_bf16_f32 v64, v68, v69
	v_cvt_pk_bf16_f32 v65, v70, v71
	v_cvt_pk_bf16_f32 v66, v74, v75
	v_cvt_pk_bf16_f32 v67, v76, v77
	global_store_dwordx4 v[72:73], v[64:67], off offset:2048
	global_load_dwordx4 v[64:67], v[160:161], off offset:528
	global_load_dwordx4 v[68:71], v[160:161], off offset:512
	v_mbcnt_lo_u32_b32 v75, -1, 0
	v_mbcnt_hi_u32_b32 v75, -1, v75
	v_and_b32_e32 v74, 15, v75
	v_lshrrev_b32_e32 v75, 4, v75
	v_mul_u32_u24_e32 v74, 0x1c00, v74
	v_readfirstlane_b32 s12, v158
	v_readfirstlane_b32 s13, v159
	v_lshl_or_b32 v74, v75, 4, v74
	s_nop 4
	global_load_dwordx4 v[178:181], v74, s[12:13] offset:2304
	s_add_u32 s12, s12, 0x1c000
	s_addc_u32 s13, s13, 0
	global_load_dwordx4 v[182:185], v74, s[12:13] offset:2304
	s_add_u32 s12, s12, 0x1c000
	s_addc_u32 s13, s13, 0
	global_load_dwordx4 v[186:189], v74, s[12:13] offset:2304
	s_add_u32 s12, s12, 0x1c000
	s_addc_u32 s13, s13, 0
	global_load_dwordx4 v[190:193], v74, s[12:13] offset:2304
	s_add_u32 s12, s12, 0x8c000
	s_addc_u32 s13, s13, 0
	global_load_dwordx4 v[194:197], v74, s[12:13] offset:2304
	s_add_u32 s12, s12, 0x1c000
	s_addc_u32 s13, s13, 0
	global_load_dwordx4 v[198:201], v74, s[12:13] offset:2304
	s_add_u32 s12, s12, 0x1c000
	s_addc_u32 s13, s13, 0
	global_load_dwordx4 v[202:205], v74, s[12:13] offset:2304
	s_add_u32 s12, s12, 0x1c000
	s_addc_u32 s13, s13, 0
	global_load_dwordx4 v[206:209], v74, s[12:13] offset:2304
	s_mov_b64 s[12:13], -1
	s_waitcnt vmcnt(7)
; __device__ __forceinline__ float bflo(unsigned w) { return __uint_as_float(w << 16); }
; __device__ __forceinline__ float bfhi(unsigned w) { return __uint_as_float(w & 0xffff0000u); }
;     __device__ __forceinline__ void operator()(const f32x4 (&acc)[2][2][4][2], const Unit& u, int wr, int wc, int fr, int fq, const LAS float* rsl) const {
;     ...
;             for (int ai = 0; ai < 2; ++ai)
; #pragma unroll
;                 for (int m = 0; m < 4; ++m) {
;                     const int row = row0 + ai * 128 + m * 16;
;                     bf16_t* ptr = P + (size_t)row * PW + 1024 + col;
;                     const u32x4 g = *(const u32x4*)ptr;
;                     f32x4 v0 = acc[ai][bj][m][0] * p0, v1 = acc[ai][bj][m][1] * p1;
;                     v0[0] *= bflo(g.x); v0[1] *= bfhi(g.x); v0[2] *= bflo(g.y); v0[3] *= bfhi(g.y);
;                     v1[0] *= bflo(g.z); v1[1] *= bfhi(g.z); v1[2] *= bflo(g.w); v1[3] *= bfhi(g.w);
;                     *(u32x4*)ptr = pack8(v0, v1);
	s_nop 1
	v_mov_b32_e32 v74, v178
	v_mov_b32_e32 v75, v179
	v_mov_b32_e32 v76, v180
	v_mov_b32_e32 v77, v181
	v_pk_mul_f32 v[56:57], v[56:57], v[64:65]
	v_pk_mul_f32 v[62:63], v[62:63], v[70:71]
	v_lshlrev_b32_e32 v78, 16, v74
	v_and_b32_e32 v79, 0xffff0000, v74
	v_lshlrev_b32_e32 v74, 16, v75
	v_and_b32_e32 v75, 0xffff0000, v75
	v_pk_mul_f32 v[62:63], v[62:63], v[74:75]
	v_lshlrev_b32_e32 v74, 16, v76
	v_and_b32_e32 v75, 0xffff0000, v76
	v_pk_mul_f32 v[60:61], v[60:61], v[68:69]
	v_pk_mul_f32 v[58:59], v[58:59], v[66:67]
	v_pk_mul_f32 v[74:75], v[56:57], v[74:75]
	v_lshlrev_b32_e32 v56, 16, v77
	v_and_b32_e32 v57, 0xffff0000, v77
	v_pk_mul_f32 v[60:61], v[60:61], v[78:79]
	v_pk_mul_f32 v[76:77], v[58:59], v[56:57]
	v_cvt_pk_bf16_f32 v56, v60, v61
	v_cvt_pk_bf16_f32 v57, v62, v63
	v_cvt_pk_bf16_f32 v58, v74, v75
	v_cvt_pk_bf16_f32 v59, v76, v77
	global_store_dwordx4 v[158:159], v[56:59], off offset:2304
	s_waitcnt vmcnt(7)
	s_nop 1
	v_mov_b32_e32 v56, v182
	v_mov_b32_e32 v57, v183
	v_mov_b32_e32 v58, v184
	v_mov_b32_e32 v59, v185
	v_pk_mul_f32 v[54:55], v[54:55], v[70:71]
	v_pk_mul_f32 v[48:49], v[48:49], v[64:65]
	v_pk_mul_f32 v[52:53], v[52:53], v[68:69]
	v_pk_mul_f32 v[50:51], v[50:51], v[66:67]
	v_pk_mul_f32 v[46:47], v[46:47], v[70:71]
	v_pk_mul_f32 v[40:41], v[40:41], v[64:65]
	v_pk_mul_f32 v[44:45], v[44:45], v[68:69]
	v_pk_mul_f32 v[42:43], v[42:43], v[66:67]
	v_pk_mul_f32 v[38:39], v[38:39], v[70:71]
	v_pk_mul_f32 v[32:33], v[32:33], v[64:65]
	v_pk_mul_f32 v[36:37], v[36:37], v[68:69]
	v_pk_mul_f32 v[34:35], v[34:35], v[66:67]
	v_pk_mul_f32 v[30:31], v[30:31], v[70:71]
	v_pk_mul_f32 v[24:25], v[24:25], v[64:65]
	v_pk_mul_f32 v[28:29], v[28:29], v[68:69]
	v_pk_mul_f32 v[26:27], v[26:27], v[66:67]
	v_pk_mul_f32 v[22:23], v[22:23], v[70:71]
	v_pk_mul_f32 v[16:17], v[16:17], v[64:65]
	v_pk_mul_f32 v[20:21], v[20:21], v[68:69]
	v_pk_mul_f32 v[18:19], v[18:19], v[66:67]
	v_pk_mul_f32 v[14:15], v[14:15], v[70:71]
	v_pk_mul_f32 v[8:9], v[8:9], v[64:65]
	v_pk_mul_f32 v[12:13], v[12:13], v[68:69]
	v_pk_mul_f32 v[10:11], v[10:11], v[66:67]
	v_pk_mul_f32 v[6:7], v[6:7], v[70:71]
	v_pk_mul_f32 v[0:1], v[0:1], v[64:65]
	v_pk_mul_f32 v[4:5], v[4:5], v[68:69]
	v_pk_mul_f32 v[2:3], v[2:3], v[66:67]
	v_lshlrev_b32_e32 v60, 16, v56
	v_and_b32_e32 v61, 0xffff0000, v56
	v_lshlrev_b32_e32 v56, 16, v57
	v_and_b32_e32 v57, 0xffff0000, v57
	v_pk_mul_f32 v[54:55], v[54:55], v[56:57]
	v_lshlrev_b32_e32 v56, 16, v58
	v_and_b32_e32 v57, 0xffff0000, v58
	v_pk_mul_f32 v[56:57], v[48:49], v[56:57]
	v_lshlrev_b32_e32 v48, 16, v59
	v_and_b32_e32 v49, 0xffff0000, v59
	v_pk_mul_f32 v[52:53], v[52:53], v[60:61]
	v_pk_mul_f32 v[58:59], v[50:51], v[48:49]
	v_cvt_pk_bf16_f32 v48, v52, v53
	v_cvt_pk_bf16_f32 v49, v54, v55
	v_cvt_pk_bf16_f32 v50, v56, v57
	v_cvt_pk_bf16_f32 v51, v58, v59
	global_store_dwordx4 v[128:129], v[48:51], off offset:2304
	s_waitcnt vmcnt(7)
	s_nop 1
	v_mov_b32_e32 v48, v186
	v_mov_b32_e32 v49, v187
	v_mov_b32_e32 v50, v188
	v_mov_b32_e32 v51, v189
	v_lshlrev_b32_e32 v52, 16, v48
	v_and_b32_e32 v53, 0xffff0000, v48
	v_lshlrev_b32_e32 v48, 16, v49
	v_and_b32_e32 v49, 0xffff0000, v49
	v_pk_mul_f32 v[46:47], v[46:47], v[48:49]
	v_lshlrev_b32_e32 v48, 16, v50
	v_and_b32_e32 v49, 0xffff0000, v50
	v_pk_mul_f32 v[48:49], v[40:41], v[48:49]
	v_lshlrev_b32_e32 v40, 16, v51
	v_and_b32_e32 v41, 0xffff0000, v51
	v_pk_mul_f32 v[44:45], v[44:45], v[52:53]
	v_pk_mul_f32 v[50:51], v[42:43], v[40:41]
	v_cvt_pk_bf16_f32 v40, v44, v45
	v_cvt_pk_bf16_f32 v41, v46, v47
	v_cvt_pk_bf16_f32 v42, v48, v49
	v_cvt_pk_bf16_f32 v43, v50, v51
	global_store_dwordx4 v[120:121], v[40:43], off offset:2304
	s_waitcnt vmcnt(7)
; __device__ __forceinline__ float bflo(unsigned w) { return __uint_as_float(w << 16); }
; __device__ __forceinline__ float bfhi(unsigned w) { return __uint_as_float(w & 0xffff0000u); }
; #define PG8_BAR __builtin_amdgcn_s_barrier()
;     ...
;         if (!has_next) break;
; #pragma unroll
;         for (int a = 0; a < 2; ++a)
; #pragma unroll
;             for (int b = 0; b < 2; ++b)
; #pragma unroll
;                 for (int m = 0; m < 4; ++m)
; #pragma unroll
;                     for (int n = 0; n < 2; ++n) acc[a][b][m][n] = (f32x4){0.f, 0.f, 0.f, 0.f};
;         cur = nxt; cA = nA; cB = nB; ++ui;
;         if constexpr (ALIGN_EPI) { if (wr == 1) PG8_BAR; }
;     __device__ __forceinline__ void operator()(const f32x4 (&acc)[2][2][4][2], const Unit& u, int wr, int wc, int fr, int fq, const LAS float* rsl) const {
;     ...
;                 for (int m = 0; m < 4; ++m) {
;                     const int row = row0 + ai * 128 + m * 16;
;                     bf16_t* ptr = P + (size_t)row * PW + 1024 + col;
;                     const u32x4 g = *(const u32x4*)ptr;
;                     f32x4 v0 = acc[ai][bj][m][0] * p0, v1 = acc[ai][bj][m][1] * p1;
;                     v0[0] *= bflo(g.x); v0[1] *= bfhi(g.x); v0[2] *= bflo(g.y); v0[3] *= bfhi(g.y);
;                     v1[0] *= bflo(g.z); v1[1] *= bfhi(g.z); v1[2] *= bflo(g.w); v1[3] *= bfhi(g.w);
;                     *(u32x4*)ptr = pack8(v0, v1);
	s_nop 1
	v_mov_b32_e32 v40, v190
	v_mov_b32_e32 v41, v191
	v_mov_b32_e32 v42, v192
	v_mov_b32_e32 v43, v193
	v_lshlrev_b32_e32 v44, 16, v40
	v_and_b32_e32 v45, 0xffff0000, v40
	v_lshlrev_b32_e32 v40, 16, v41
	v_and_b32_e32 v41, 0xffff0000, v41
	v_pk_mul_f32 v[38:39], v[38:39], v[40:41]
	v_lshlrev_b32_e32 v40, 16, v42
	v_and_b32_e32 v41, 0xffff0000, v42
	v_pk_mul_f32 v[40:41], v[32:33], v[40:41]
	v_lshlrev_b32_e32 v32, 16, v43
	v_and_b32_e32 v33, 0xffff0000, v43
	v_pk_mul_f32 v[36:37], v[36:37], v[44:45]
	v_pk_mul_f32 v[42:43], v[34:35], v[32:33]
	v_cvt_pk_bf16_f32 v32, v36, v37
	v_cvt_pk_bf16_f32 v33, v38, v39
	v_cvt_pk_bf16_f32 v34, v40, v41
	v_cvt_pk_bf16_f32 v35, v42, v43
	global_store_dwordx4 v[104:105], v[32:35], off offset:2304
	s_waitcnt vmcnt(7)
	s_nop 1
	v_mov_b32_e32 v32, v194
	v_mov_b32_e32 v33, v195
	v_mov_b32_e32 v34, v196
	v_mov_b32_e32 v35, v197
	v_lshlrev_b32_e32 v36, 16, v32
	v_and_b32_e32 v37, 0xffff0000, v32
	v_lshlrev_b32_e32 v32, 16, v33
	v_and_b32_e32 v33, 0xffff0000, v33
	v_pk_mul_f32 v[30:31], v[30:31], v[32:33]
	v_lshlrev_b32_e32 v32, 16, v34
	v_and_b32_e32 v33, 0xffff0000, v34
	v_pk_mul_f32 v[32:33], v[24:25], v[32:33]
	v_lshlrev_b32_e32 v24, 16, v35
	v_and_b32_e32 v25, 0xffff0000, v35
	v_pk_mul_f32 v[28:29], v[28:29], v[36:37]
	v_pk_mul_f32 v[34:35], v[26:27], v[24:25]
	v_cvt_pk_bf16_f32 v24, v28, v29
	v_cvt_pk_bf16_f32 v25, v30, v31
	v_cvt_pk_bf16_f32 v26, v32, v33
	v_cvt_pk_bf16_f32 v27, v34, v35
	global_store_dwordx4 v[96:97], v[24:27], off offset:2304
	s_waitcnt vmcnt(7)
	s_nop 1
	v_mov_b32_e32 v24, v198
	v_mov_b32_e32 v25, v199
	v_mov_b32_e32 v26, v200
	v_mov_b32_e32 v27, v201
	v_lshlrev_b32_e32 v28, 16, v24
	v_and_b32_e32 v29, 0xffff0000, v24
	v_lshlrev_b32_e32 v24, 16, v25
	v_and_b32_e32 v25, 0xffff0000, v25
	v_pk_mul_f32 v[22:23], v[22:23], v[24:25]
	v_lshlrev_b32_e32 v24, 16, v26
	v_and_b32_e32 v25, 0xffff0000, v26
	v_pk_mul_f32 v[24:25], v[16:17], v[24:25]
	v_lshlrev_b32_e32 v16, 16, v27
	v_and_b32_e32 v17, 0xffff0000, v27
	v_pk_mul_f32 v[20:21], v[20:21], v[28:29]
	v_pk_mul_f32 v[26:27], v[18:19], v[16:17]
	v_cvt_pk_bf16_f32 v16, v20, v21
	v_cvt_pk_bf16_f32 v17, v22, v23
	v_cvt_pk_bf16_f32 v18, v24, v25
	v_cvt_pk_bf16_f32 v19, v26, v27
	global_store_dwordx4 v[88:89], v[16:19], off offset:2304
	s_waitcnt vmcnt(7)
	s_nop 1
	v_mov_b32_e32 v16, v202
	v_mov_b32_e32 v17, v203
	v_mov_b32_e32 v18, v204
	v_mov_b32_e32 v19, v205
	v_lshlrev_b32_e32 v20, 16, v16
	v_and_b32_e32 v21, 0xffff0000, v16
	v_lshlrev_b32_e32 v16, 16, v17
	v_and_b32_e32 v17, 0xffff0000, v17
	v_pk_mul_f32 v[14:15], v[14:15], v[16:17]
	v_lshlrev_b32_e32 v16, 16, v18
	v_and_b32_e32 v17, 0xffff0000, v18
	v_pk_mul_f32 v[16:17], v[8:9], v[16:17]
	v_lshlrev_b32_e32 v8, 16, v19
	v_and_b32_e32 v9, 0xffff0000, v19
	v_pk_mul_f32 v[12:13], v[12:13], v[20:21]
	v_pk_mul_f32 v[18:19], v[10:11], v[8:9]
	v_cvt_pk_bf16_f32 v8, v12, v13
	v_cvt_pk_bf16_f32 v9, v14, v15
	v_cvt_pk_bf16_f32 v10, v16, v17
	v_cvt_pk_bf16_f32 v11, v18, v19
	global_store_dwordx4 v[80:81], v[8:11], off offset:2304
	s_waitcnt vmcnt(7)
	s_nop 1
	v_mov_b32_e32 v8, v206
	v_mov_b32_e32 v9, v207
	v_mov_b32_e32 v10, v208
	v_mov_b32_e32 v11, v209
	v_lshlrev_b32_e32 v12, 16, v8
	v_and_b32_e32 v13, 0xffff0000, v8
	v_lshlrev_b32_e32 v8, 16, v9
	v_and_b32_e32 v9, 0xffff0000, v9
	v_pk_mul_f32 v[6:7], v[6:7], v[8:9]
	v_lshlrev_b32_e32 v8, 16, v10
	v_and_b32_e32 v9, 0xffff0000, v10
	v_pk_mul_f32 v[8:9], v[0:1], v[8:9]
	v_lshlrev_b32_e32 v0, 16, v11
	v_and_b32_e32 v1, 0xffff0000, v11
	v_pk_mul_f32 v[4:5], v[4:5], v[12:13]
	v_pk_mul_f32 v[10:11], v[2:3], v[0:1]
	v_cvt_pk_bf16_f32 v0, v4, v5
	v_cvt_pk_bf16_f32 v1, v6, v7
	v_cvt_pk_bf16_f32 v2, v8, v9
	v_cvt_pk_bf16_f32 v3, v10, v11
	global_store_dwordx4 v[72:73], v[0:3], off offset:2304
	s_cbranch_vccnz .LBB0_274
	s_andn2_b64 vcc, exec, s[0:1]
	s_cbranch_vccnz .LBB0_273
	s_barrier
	s_branch .LBB0_273
